# v20 with the P3 apply-loop output stores write-through (sc0 sc1) instead of nt
# speedup vs baseline: 1.0005x; 1.0005x over previous
.LBB0_1125:
	s_or_b64 exec, exec, s[30:31]
	s_and_b64 s[8:9], s[80:81], exec
	s_cselect_b32 s9, s13, s19
	s_cselect_b32 s8, s12, s18
	s_lshl_b64 s[12:13], s[90:91], 12
	s_add_u32 s12, s16, s12
	s_addc_u32 s13, s17, s13
	s_lshl_b32 s16, s25, 5
	s_lshl_b32 s17, s26, 8
	s_or_b32 s16, s17, s16
	v_lshrrev_b32_e32 v0, 2, v140
	v_add_u32_e32 v134, s27, v141
	v_and_or_b32 v0, v0, 12, s16
	v_ashrrev_i32_e32 v135, 31, v134
	v_ashrrev_i32_e32 v1, 31, v0
	v_lshlrev_b64 v[136:137], 10, v[134:135]
	s_waitcnt lgkmcnt(0)
	v_lshl_add_u32 v2, v141, 2, 0
	v_lshl_add_u64 v[140:141], v[136:137], 0, v[0:1]
	v_lshlrev_b64 v[146:147], 2, v[140:141]
	s_waitcnt lgkmcnt(0)
	s_barrier
	v_lshlrev_b32_e32 v144, 2, v0
	global_load_dwordx4 v[224:227], v144, s[12:13]
	global_load_dwordx2 v[196:197], v144, s[12:13] offset:64
	global_load_dwordx2 v[200:201], v144, s[12:13] offset:72
	global_load_dwordx2 v[228:229], v144, s[12:13] offset:512
	global_load_dwordx2 v[250:251], v144, s[12:13] offset:520
	global_load_dwordx2 v[254:255], v144, s[12:13] offset:576
	global_load_dwordx2 v[180:181], v144, s[12:13] offset:584
	global_load_dwordx4 v[136:139], v146, s[8:9] nt
	global_load_dwordx4 v[140:143], v146, s[8:9] offset:64 nt
	global_load_dwordx4 v[148:151], v146, s[8:9] offset:512 nt
	global_load_dwordx4 v[168:171], v146, s[8:9] offset:576 nt
	v_add_u32_e32 v198, 0x10000, v146
	global_load_dwordx4 v[172:175], v198, s[8:9] nt
	global_load_dwordx4 v[176:179], v198, s[8:9] offset:64 nt
	global_load_dwordx4 v[242:245], v198, s[8:9] offset:512 nt
	global_load_dwordx4 v[246:249], v198, s[8:9] offset:576 nt
	ds_read_b32 v190, v2 offset:8192
	ds_read_b32 v192, v2 offset:8256
	s_waitcnt lgkmcnt(1)
	v_pk_mul_f32 v[100:101], v[100:101], v[190:191] op_sel_hi:[1,0]
	v_pk_mul_f32 v[102:103], v[102:103], v[190:191] op_sel_hi:[1,0]
	v_pk_mul_f32 v[120:121], v[120:121], v[190:191] op_sel_hi:[1,0]
	v_pk_mul_f32 v[122:123], v[122:123], v[190:191] op_sel_hi:[1,0]
	v_pk_mul_f32 v[116:117], v[116:117], v[190:191] op_sel_hi:[1,0]
	v_pk_mul_f32 v[118:119], v[118:119], v[190:191] op_sel_hi:[1,0]
	v_pk_mul_f32 v[108:109], v[108:109], v[190:191] op_sel_hi:[1,0]
	v_pk_mul_f32 v[110:111], v[110:111], v[190:191] op_sel_hi:[1,0]
	s_waitcnt vmcnt(4)
	v_pk_fma_f32 v[100:101], v[224:225], v[100:101], v[136:137]
	v_pk_fma_f32 v[102:103], v[226:227], v[102:103], v[138:139]
	v_pk_fma_f32 v[120:121], v[196:197], v[120:121], v[140:141]
	v_pk_fma_f32 v[122:123], v[200:201], v[122:123], v[142:143]
	v_pk_fma_f32 v[116:117], v[228:229], v[116:117], v[148:149]
	v_pk_fma_f32 v[118:119], v[250:251], v[118:119], v[150:151]
	v_pk_fma_f32 v[108:109], v[254:255], v[108:109], v[168:169]
	v_pk_fma_f32 v[110:111], v[180:181], v[110:111], v[170:171]
	global_store_dwordx4 v146, v[100:103], s[18:19] sc0 sc1
	global_store_dwordx4 v146, v[120:123], s[18:19] offset:64 sc0 sc1
	global_store_dwordx4 v146, v[116:119], s[18:19] offset:512 sc0 sc1
	global_store_dwordx4 v146, v[108:111], s[18:19] offset:576 sc0 sc1
	v_add_u32_e32 v198, 0x20000, v146
	global_load_dwordx4 v[136:139], v198, s[8:9] nt
	global_load_dwordx4 v[140:143], v198, s[8:9] offset:64 nt
	global_load_dwordx4 v[148:151], v198, s[8:9] offset:512 nt
	global_load_dwordx4 v[168:171], v198, s[8:9] offset:576 nt
	ds_read_b32 v190, v2 offset:8320
	s_waitcnt lgkmcnt(1)
	v_pk_mul_f32 v[128:129], v[128:129], v[192:193] op_sel_hi:[1,0]
	v_pk_mul_f32 v[130:131], v[130:131], v[192:193] op_sel_hi:[1,0]
	v_pk_mul_f32 v[124:125], v[124:125], v[192:193] op_sel_hi:[1,0]
	v_pk_mul_f32 v[126:127], v[126:127], v[192:193] op_sel_hi:[1,0]
	v_pk_mul_f32 v[112:113], v[112:113], v[192:193] op_sel_hi:[1,0]
	v_pk_mul_f32 v[114:115], v[114:115], v[192:193] op_sel_hi:[1,0]
	v_pk_mul_f32 v[104:105], v[104:105], v[192:193] op_sel_hi:[1,0]
	v_pk_mul_f32 v[106:107], v[106:107], v[192:193] op_sel_hi:[1,0]
	s_waitcnt vmcnt(8)
	v_pk_fma_f32 v[128:129], v[224:225], v[128:129], v[172:173]
	v_pk_fma_f32 v[130:131], v[226:227], v[130:131], v[174:175]
	v_pk_fma_f32 v[124:125], v[196:197], v[124:125], v[176:177]
	v_pk_fma_f32 v[126:127], v[200:201], v[126:127], v[178:179]
	v_pk_fma_f32 v[112:113], v[228:229], v[112:113], v[242:243]
	v_pk_fma_f32 v[114:115], v[250:251], v[114:115], v[244:245]
	v_pk_fma_f32 v[104:105], v[254:255], v[104:105], v[246:247]
	v_pk_fma_f32 v[106:107], v[180:181], v[106:107], v[248:249]
	v_add_u32_e32 v145, 0x10000, v146
	global_store_dwordx4 v145, v[128:131], s[18:19] sc0 sc1
	global_store_dwordx4 v145, v[124:127], s[18:19] offset:64 sc0 sc1
	global_store_dwordx4 v145, v[112:115], s[18:19] offset:512 sc0 sc1
	global_store_dwordx4 v145, v[104:107], s[18:19] offset:576 sc0 sc1
	v_add_u32_e32 v198, 0x30000, v146
	global_load_dwordx4 v[172:175], v198, s[8:9] nt
	global_load_dwordx4 v[176:179], v198, s[8:9] offset:64 nt
	global_load_dwordx4 v[242:245], v198, s[8:9] offset:512 nt
	global_load_dwordx4 v[246:249], v198, s[8:9] offset:576 nt
	ds_read_b32 v192, v2 offset:8384
	s_waitcnt lgkmcnt(1)
	v_pk_mul_f32 v[96:97], v[96:97], v[190:191] op_sel_hi:[1,0]
	v_pk_mul_f32 v[98:99], v[98:99], v[190:191] op_sel_hi:[1,0]
	v_pk_mul_f32 v[92:93], v[92:93], v[190:191] op_sel_hi:[1,0]
	v_pk_mul_f32 v[94:95], v[94:95], v[190:191] op_sel_hi:[1,0]
	v_pk_mul_f32 v[88:89], v[88:89], v[190:191] op_sel_hi:[1,0]
	v_pk_mul_f32 v[90:91], v[90:91], v[190:191] op_sel_hi:[1,0]
	v_pk_mul_f32 v[84:85], v[84:85], v[190:191] op_sel_hi:[1,0]
	v_pk_mul_f32 v[86:87], v[86:87], v[190:191] op_sel_hi:[1,0]
	s_waitcnt vmcnt(8)
	v_pk_fma_f32 v[96:97], v[224:225], v[96:97], v[136:137]
	v_pk_fma_f32 v[98:99], v[226:227], v[98:99], v[138:139]
	v_pk_fma_f32 v[92:93], v[196:197], v[92:93], v[140:141]
	v_pk_fma_f32 v[94:95], v[200:201], v[94:95], v[142:143]
	v_pk_fma_f32 v[88:89], v[228:229], v[88:89], v[148:149]
	v_pk_fma_f32 v[90:91], v[250:251], v[90:91], v[150:151]
	v_pk_fma_f32 v[84:85], v[254:255], v[84:85], v[168:169]
	v_pk_fma_f32 v[86:87], v[180:181], v[86:87], v[170:171]
	v_add_u32_e32 v145, 0x20000, v146
	global_store_dwordx4 v145, v[96:99], s[18:19] sc0 sc1
	global_store_dwordx4 v145, v[92:95], s[18:19] offset:64 sc0 sc1
	global_store_dwordx4 v145, v[88:91], s[18:19] offset:512 sc0 sc1
	global_store_dwordx4 v145, v[84:87], s[18:19] offset:576 sc0 sc1
	v_add_u32_e32 v198, 0x80000, v146
	global_load_dwordx4 v[136:139], v198, s[8:9] nt
	global_load_dwordx4 v[140:143], v198, s[8:9] offset:64 nt
	global_load_dwordx4 v[148:151], v198, s[8:9] offset:512 nt
	global_load_dwordx4 v[168:171], v198, s[8:9] offset:576 nt
	ds_read_b32 v190, v2 offset:8704
	s_waitcnt lgkmcnt(1)
	v_pk_mul_f32 v[80:81], v[80:81], v[192:193] op_sel_hi:[1,0]
	v_pk_mul_f32 v[82:83], v[82:83], v[192:193] op_sel_hi:[1,0]
	v_pk_mul_f32 v[76:77], v[76:77], v[192:193] op_sel_hi:[1,0]
	v_pk_mul_f32 v[78:79], v[78:79], v[192:193] op_sel_hi:[1,0]
	v_pk_mul_f32 v[72:73], v[72:73], v[192:193] op_sel_hi:[1,0]
	v_pk_mul_f32 v[74:75], v[74:75], v[192:193] op_sel_hi:[1,0]
	v_pk_mul_f32 v[68:69], v[68:69], v[192:193] op_sel_hi:[1,0]
	v_pk_mul_f32 v[70:71], v[70:71], v[192:193] op_sel_hi:[1,0]
	s_waitcnt vmcnt(8)
	v_pk_fma_f32 v[80:81], v[224:225], v[80:81], v[172:173]
	v_pk_fma_f32 v[82:83], v[226:227], v[82:83], v[174:175]
	v_pk_fma_f32 v[76:77], v[196:197], v[76:77], v[176:177]
	v_pk_fma_f32 v[78:79], v[200:201], v[78:79], v[178:179]
	v_pk_fma_f32 v[72:73], v[228:229], v[72:73], v[242:243]
	v_pk_fma_f32 v[74:75], v[250:251], v[74:75], v[244:245]
	v_pk_fma_f32 v[68:69], v[254:255], v[68:69], v[246:247]
	v_pk_fma_f32 v[70:71], v[180:181], v[70:71], v[248:249]
	v_add_u32_e32 v145, 0x30000, v146
	global_store_dwordx4 v145, v[80:83], s[18:19] sc0 sc1
	global_store_dwordx4 v145, v[76:79], s[18:19] offset:64 sc0 sc1
	global_store_dwordx4 v145, v[72:75], s[18:19] offset:512 sc0 sc1
	global_store_dwordx4 v145, v[68:71], s[18:19] offset:576 sc0 sc1
	v_add_u32_e32 v198, 0x90000, v146
	global_load_dwordx4 v[172:175], v198, s[8:9] nt
	global_load_dwordx4 v[176:179], v198, s[8:9] offset:64 nt
	global_load_dwordx4 v[242:245], v198, s[8:9] offset:512 nt
	global_load_dwordx4 v[246:249], v198, s[8:9] offset:576 nt
	ds_read_b32 v192, v2 offset:8768
	s_waitcnt lgkmcnt(1)
	v_pk_mul_f32 v[64:65], v[64:65], v[190:191] op_sel_hi:[1,0]
	v_pk_mul_f32 v[66:67], v[66:67], v[190:191] op_sel_hi:[1,0]
	v_pk_mul_f32 v[60:61], v[60:61], v[190:191] op_sel_hi:[1,0]
	v_pk_mul_f32 v[62:63], v[62:63], v[190:191] op_sel_hi:[1,0]
	v_pk_mul_f32 v[56:57], v[56:57], v[190:191] op_sel_hi:[1,0]
	v_pk_mul_f32 v[58:59], v[58:59], v[190:191] op_sel_hi:[1,0]
	v_pk_mul_f32 v[52:53], v[52:53], v[190:191] op_sel_hi:[1,0]
	v_pk_mul_f32 v[54:55], v[54:55], v[190:191] op_sel_hi:[1,0]
	s_waitcnt vmcnt(8)
	v_pk_fma_f32 v[64:65], v[224:225], v[64:65], v[136:137]
	v_pk_fma_f32 v[66:67], v[226:227], v[66:67], v[138:139]
	v_pk_fma_f32 v[60:61], v[196:197], v[60:61], v[140:141]
	v_pk_fma_f32 v[62:63], v[200:201], v[62:63], v[142:143]
	v_pk_fma_f32 v[56:57], v[228:229], v[56:57], v[148:149]
	v_pk_fma_f32 v[58:59], v[250:251], v[58:59], v[150:151]
	v_pk_fma_f32 v[52:53], v[254:255], v[52:53], v[168:169]
	v_pk_fma_f32 v[54:55], v[180:181], v[54:55], v[170:171]
	v_add_u32_e32 v145, 0x80000, v146
	global_store_dwordx4 v145, v[64:67], s[18:19] sc0 sc1
	global_store_dwordx4 v145, v[60:63], s[18:19] offset:64 sc0 sc1
	global_store_dwordx4 v145, v[56:59], s[18:19] offset:512 sc0 sc1
	global_store_dwordx4 v145, v[52:55], s[18:19] offset:576 sc0 sc1
	v_add_u32_e32 v198, 0xa0000, v146
	global_load_dwordx4 v[136:139], v198, s[8:9] nt
	global_load_dwordx4 v[140:143], v198, s[8:9] offset:64 nt
	global_load_dwordx4 v[148:151], v198, s[8:9] offset:512 nt
	global_load_dwordx4 v[168:171], v198, s[8:9] offset:576 nt
	ds_read_b32 v190, v2 offset:8832
	s_waitcnt lgkmcnt(1)
	v_pk_mul_f32 v[48:49], v[48:49], v[192:193] op_sel_hi:[1,0]
	v_pk_mul_f32 v[50:51], v[50:51], v[192:193] op_sel_hi:[1,0]
	v_pk_mul_f32 v[44:45], v[44:45], v[192:193] op_sel_hi:[1,0]
	v_pk_mul_f32 v[46:47], v[46:47], v[192:193] op_sel_hi:[1,0]
	v_pk_mul_f32 v[40:41], v[40:41], v[192:193] op_sel_hi:[1,0]
	v_pk_mul_f32 v[42:43], v[42:43], v[192:193] op_sel_hi:[1,0]
	v_pk_mul_f32 v[36:37], v[36:37], v[192:193] op_sel_hi:[1,0]
	v_pk_mul_f32 v[38:39], v[38:39], v[192:193] op_sel_hi:[1,0]
	s_waitcnt vmcnt(8)
	v_pk_fma_f32 v[48:49], v[224:225], v[48:49], v[172:173]
	v_pk_fma_f32 v[50:51], v[226:227], v[50:51], v[174:175]
	v_pk_fma_f32 v[44:45], v[196:197], v[44:45], v[176:177]
	v_pk_fma_f32 v[46:47], v[200:201], v[46:47], v[178:179]
	v_pk_fma_f32 v[40:41], v[228:229], v[40:41], v[242:243]
	v_pk_fma_f32 v[42:43], v[250:251], v[42:43], v[244:245]
	v_pk_fma_f32 v[36:37], v[254:255], v[36:37], v[246:247]
	v_pk_fma_f32 v[38:39], v[180:181], v[38:39], v[248:249]
	v_add_u32_e32 v145, 0x90000, v146
	global_store_dwordx4 v145, v[48:51], s[18:19] sc0 sc1
	global_store_dwordx4 v145, v[44:47], s[18:19] offset:64 sc0 sc1
	global_store_dwordx4 v145, v[40:43], s[18:19] offset:512 sc0 sc1
	global_store_dwordx4 v145, v[36:39], s[18:19] offset:576 sc0 sc1
	v_add_u32_e32 v198, 0xb0000, v146
	global_load_dwordx4 v[172:175], v198, s[8:9] nt
	global_load_dwordx4 v[176:179], v198, s[8:9] offset:64 nt
	global_load_dwordx4 v[242:245], v198, s[8:9] offset:512 nt
	global_load_dwordx4 v[246:249], v198, s[8:9] offset:576 nt
	ds_read_b32 v192, v2 offset:8896
	s_waitcnt lgkmcnt(1)
	v_pk_mul_f32 v[32:33], v[32:33], v[190:191] op_sel_hi:[1,0]
	v_pk_mul_f32 v[34:35], v[34:35], v[190:191] op_sel_hi:[1,0]
	v_pk_mul_f32 v[28:29], v[28:29], v[190:191] op_sel_hi:[1,0]
	v_pk_mul_f32 v[30:31], v[30:31], v[190:191] op_sel_hi:[1,0]
	v_pk_mul_f32 v[24:25], v[24:25], v[190:191] op_sel_hi:[1,0]
	v_pk_mul_f32 v[26:27], v[26:27], v[190:191] op_sel_hi:[1,0]
	v_pk_mul_f32 v[20:21], v[20:21], v[190:191] op_sel_hi:[1,0]
	v_pk_mul_f32 v[22:23], v[22:23], v[190:191] op_sel_hi:[1,0]
	s_waitcnt vmcnt(8)
	v_pk_fma_f32 v[32:33], v[224:225], v[32:33], v[136:137]
	v_pk_fma_f32 v[34:35], v[226:227], v[34:35], v[138:139]
	v_pk_fma_f32 v[28:29], v[196:197], v[28:29], v[140:141]
	v_pk_fma_f32 v[30:31], v[200:201], v[30:31], v[142:143]
	v_pk_fma_f32 v[24:25], v[228:229], v[24:25], v[148:149]
	v_pk_fma_f32 v[26:27], v[250:251], v[26:27], v[150:151]
	v_pk_fma_f32 v[20:21], v[254:255], v[20:21], v[168:169]
	v_pk_fma_f32 v[22:23], v[180:181], v[22:23], v[170:171]
	v_add_u32_e32 v145, 0xa0000, v146
	global_store_dwordx4 v145, v[32:35], s[18:19] sc0 sc1
	global_store_dwordx4 v145, v[28:31], s[18:19] offset:64 sc0 sc1
	global_store_dwordx4 v145, v[24:27], s[18:19] offset:512 sc0 sc1
	global_store_dwordx4 v145, v[20:23], s[18:19] offset:576 sc0 sc1
	s_waitcnt lgkmcnt(0)
	v_pk_mul_f32 v[16:17], v[16:17], v[192:193] op_sel_hi:[1,0]
	v_pk_mul_f32 v[18:19], v[18:19], v[192:193] op_sel_hi:[1,0]
	v_pk_mul_f32 v[12:13], v[12:13], v[192:193] op_sel_hi:[1,0]
	v_pk_mul_f32 v[14:15], v[14:15], v[192:193] op_sel_hi:[1,0]
	v_pk_mul_f32 v[8:9], v[8:9], v[192:193] op_sel_hi:[1,0]
	v_pk_mul_f32 v[10:11], v[10:11], v[192:193] op_sel_hi:[1,0]
	v_pk_mul_f32 v[4:5], v[4:5], v[192:193] op_sel_hi:[1,0]
	v_pk_mul_f32 v[6:7], v[6:7], v[192:193] op_sel_hi:[1,0]
	s_waitcnt vmcnt(4)
	v_pk_fma_f32 v[16:17], v[224:225], v[16:17], v[172:173]
	v_pk_fma_f32 v[18:19], v[226:227], v[18:19], v[174:175]
	v_pk_fma_f32 v[12:13], v[196:197], v[12:13], v[176:177]
	v_pk_fma_f32 v[14:15], v[200:201], v[14:15], v[178:179]
	v_pk_fma_f32 v[8:9], v[228:229], v[8:9], v[242:243]
	v_pk_fma_f32 v[10:11], v[250:251], v[10:11], v[244:245]
	v_pk_fma_f32 v[4:5], v[254:255], v[4:5], v[246:247]
	v_pk_fma_f32 v[6:7], v[180:181], v[6:7], v[248:249]
	v_add_u32_e32 v145, 0xb0000, v146
	global_store_dwordx4 v145, v[16:19], s[18:19] sc0 sc1
	global_store_dwordx4 v145, v[12:15], s[18:19] offset:64 sc0 sc1
	global_store_dwordx4 v145, v[8:11], s[18:19] offset:512 sc0 sc1
	global_store_dwordx4 v145, v[4:7], s[18:19] offset:576 sc0 sc1
	s_mov_b64 s[8:9], 0
	s_andn2_b64 vcc, exec, s[80:81]
	s_nop 1
	s_cbranch_vccnz .LBB0_1162
	v_mul_f32_e32 v150, v101, v101
	v_mul_f32_e32 v151, v103, v103
	v_fmac_f32_e32 v150, v100, v100
	v_fmac_f32_e32 v151, v102, v102
	v_add_f32_e32 v150, v150, v151
	v_mul_f32_e32 v151, v121, v121
	v_mul_f32_e32 v161, v123, v123
	v_fmac_f32_e32 v151, v120, v120
	v_fmac_f32_e32 v161, v122, v122
	v_add_f32_e32 v151, v151, v161
	v_add_f32_e32 v150, v150, v151
	v_mul_f32_e32 v151, v117, v117
	v_mul_f32_e32 v161, v119, v119
	v_fmac_f32_e32 v151, v116, v116
	v_fmac_f32_e32 v161, v118, v118
	v_add_f32_e32 v151, v151, v161
	v_add_f32_e32 v150, v151, v150
	v_mul_f32_e32 v151, v109, v109
	v_mul_f32_e32 v161, v111, v111
	v_fmac_f32_e32 v151, v108, v108
	v_fmac_f32_e32 v161, v110, v110
	v_add_f32_e32 v151, v151, v161
	v_add_f32_e32 v150, v151, v150
	ds_bpermute_b32 v151, v153, v150
	s_waitcnt lgkmcnt(0)
	v_add_f32_e32 v150, v150, v151
	ds_bpermute_b32 v151, v154, v150
	s_and_saveexec_b64 s[8:9], s[2:3]
	s_cbranch_execz .LBB0_1128
	s_lshl_b32 s12, s0, 10
	s_add_i32 s12, s1, s12
	v_lshl_add_u32 v161, v152, 4, s12
	s_waitcnt lgkmcnt(0)
	v_add_f32_e32 v150, v150, v151
	ds_write_b32 v161, v150
